# scan: the next chunk's LDS-DMA pieces are issued right after each half-phase's LDS reads (under their latency) instead of between the LDS write and the barrier
# speedup vs baseline: 1.0075x; 1.0030x over previous
.Lscan_loop:
	s_and_b32 s7, s6, 3
	s_lshl_b32 s7, s7, 12
	v_add_u32_e32 v23, s7, v22
	ds_read_b128 v[32:35], v10 offset:0
	ds_read_b128 v[48:51], v11 offset:0
	ds_read_b128 v[36:39], v10 offset:64
	ds_read_b128 v[52:55], v12 offset:0
	ds_read_b128 v[40:43], v10 offset:128
	ds_read_b128 v[56:59], v13 offset:0
	ds_read_b128 v[44:47], v10 offset:192
	ds_read_b128 v[60:63], v14 offset:0
	ds_read_u16 v80, v23 offset:0
	ds_read_u16 v81, v23 offset:64
	ds_read_u16 v82, v23 offset:128
	ds_read_u16 v83, v23 offset:192
	s_add_u32 s33, s6, 1
	s_min_u32 s33, s33, 31
	s_add_u32 s36, s6, 2
	s_min_u32 s36, s36, 31
	s_lshl_b32 s7, s33, 14
	s_add_u32 s26, s14, s7
	s_addc_u32 s27, s15, 0
	s_add_i32 m0, s30, 0x14000
	s_nop 0
	global_load_lds_dwordx4 v5, s[26:27]
	s_add_i32 m0, s30, 0x14400
	s_nop 0
	global_load_lds_dwordx4 v6, s[26:27]
	s_lshl_b32 s7, s33, 13
	s_add_u32 s28, s18, s7
	s_addc_u32 s29, s19, 0
	s_add_i32 m0, s31, 0x1a000
	s_nop 0
	global_load_lds_dwordx4 v7, s[28:29]
	s_lshl_b32 s7, s36, 14
	s_add_u32 s26, s24, s7
	s_addc_u32 s27, s25, 0
	s_add_u32 s8, s6, 2
	s_and_b32 s8, s8, 3
	s_lshl_b32 s8, s8, 12
	s_add_u32 s8, s8, s32
	s_add_i32 m0, s8, 0x1f400
	s_nop 0
	global_load_lds_dwordx4 v8, s[26:27]
	v_readlane_b32 s37, v24, s6
	s_nop 1
	v_mul_f32_e32 v92, s37, v92
	v_mul_f32_e32 v93, s37, v93
	v_mul_f32_e32 v94, s37, v94
	v_mul_f32_e32 v95, s37, v95
	v_mul_f32_e32 v96, s37, v96
	v_mul_f32_e32 v97, s37, v97
	v_mul_f32_e32 v98, s37, v98
	v_mul_f32_e32 v99, s37, v99
	s_waitcnt lgkmcnt(10)
	v_mfma_f32_16x16x32_bf16 v[84:87], v[48:51], v[32:35], 0
	s_waitcnt lgkmcnt(8)
	v_mfma_f32_16x16x32_bf16 v[84:87], v[52:55], v[36:39], v[84:87]
	s_waitcnt lgkmcnt(6)
	v_mfma_f32_16x16x32_bf16 v[84:87], v[56:59], v[40:43], v[84:87]
	s_waitcnt lgkmcnt(4)
	v_mfma_f32_16x16x32_bf16 v[84:87], v[60:63], v[44:47], v[84:87]
	ds_read_b128 v[64:67], v11 offset:32768
	ds_read_b128 v[68:71], v12 offset:32768
	ds_read_b128 v[72:75], v13 offset:32768
	ds_read_b128 v[76:79], v14 offset:32768
	s_waitcnt lgkmcnt(4)
	v_lshlrev_b32_e32 v80, 16, v80
	v_lshlrev_b32_e32 v81, 16, v81
	v_lshlrev_b32_e32 v82, 16, v82
	v_lshlrev_b32_e32 v83, 16, v83
	v_sub_f32_e32 v26, v80, v84
	v_sub_f32_e32 v27, v81, v85
	v_sub_f32_e32 v28, v82, v86
	v_sub_f32_e32 v29, v83, v87
	v_cvt_pk_bf16_f32 v26, v26, v27
	v_cvt_pk_bf16_f32 v27, v28, v29
	ds_write_b64 v20, v[26:27]
	s_waitcnt vmcnt(10) lgkmcnt(0)
	s_barrier
	ds_read_b128 v[100:103], v19
	ds_read_b128 v[108:111], v15 offset:0
	ds_read_b128 v[112:115], v15 offset:2048
	ds_read_b128 v[104:107], v19 offset:64
	ds_read_b128 v[116:119], v16 offset:0
	ds_read_b128 v[120:123], v16 offset:2048
	ds_read_b128 v[124:127], v17 offset:0
	ds_read_b128 v[128:131], v18 offset:0
	s_lshl_b32 s7, s36, 14
	s_add_u32 s26, s10, s7
	s_addc_u32 s27, s11, 0
	s_add_i32 m0, s30, 0x0
	s_nop 0
	global_load_lds_dwordx4 v3, s[26:27]
	s_add_i32 m0, s30, 0x400
	s_nop 0
	global_load_lds_dwordx4 v4, s[26:27]
	s_lshl_b32 s7, s36, 14
	s_add_u32 s26, s12, s7
	s_addc_u32 s27, s13, 0
	s_add_i32 m0, s30, 0x8000
	s_nop 0
	global_load_lds_dwordx4 v3, s[26:27]
	s_add_i32 m0, s30, 0x8400
	s_nop 0
	global_load_lds_dwordx4 v4, s[26:27]
	v_mfma_f32_16x16x32_bf16 v[88:91], v[32:35], v[64:67], 0
	v_mfma_f32_16x16x32_bf16 v[88:91], v[36:39], v[68:71], v[88:91]
	v_mfma_f32_16x16x32_bf16 v[88:91], v[40:43], v[72:75], v[88:91]
	v_mfma_f32_16x16x32_bf16 v[88:91], v[44:47], v[76:79], v[88:91]
	s_waitcnt lgkmcnt(6)
	v_mfma_f32_16x16x32_bf16 v[92:95], v[108:111], v[100:103], v[92:95]
	s_waitcnt lgkmcnt(5)
	v_mfma_f32_16x16x32_bf16 v[96:99], v[112:115], v[100:103], v[96:99]
	s_waitcnt lgkmcnt(3)
	v_mfma_f32_16x16x32_bf16 v[92:95], v[116:119], v[104:107], v[92:95]
	s_waitcnt lgkmcnt(2)
	v_mfma_f32_16x16x32_bf16 v[96:99], v[120:123], v[104:107], v[96:99]
	s_waitcnt lgkmcnt(1)
	v_mfma_f32_16x16x32_bf16 v[88:91], v[100:103], v[124:127], v[88:91]
	s_waitcnt lgkmcnt(0)
	v_mfma_f32_16x16x32_bf16 v[88:91], v[104:107], v[128:131], v[88:91]
	s_lshl_b32 s7, s6, 14
	s_add_u32 s28, s24, s7
	s_addc_u32 s29, s25, 0
	s_nop 1
	v_cvt_pk_bf16_f32 v26, v92, v93
	v_cvt_pk_bf16_f32 v27, v94, v95
	v_cvt_pk_bf16_f32 v28, v96, v97
	v_cvt_pk_bf16_f32 v29, v98, v99
	ds_write_b64 v21, v[26:27]
	ds_write_b64 v21, v[28:29] offset:32
	v_cvt_pk_bf16_f32 v80, v88, v89
	v_cvt_pk_bf16_f32 v81, v90, v91
	global_store_dwordx2 v9, v[80:81], s[28:29]
	s_add_u32 s6, s6, 1
	s_waitcnt vmcnt(10) lgkmcnt(0)
	s_barrier
	s_and_b32 s7, s6, 3
	s_lshl_b32 s7, s7, 12
	v_add_u32_e32 v23, s7, v22
	ds_read_b128 v[32:35], v10 offset:0
	ds_read_b128 v[48:51], v11 offset:16384
	ds_read_b128 v[36:39], v10 offset:64
	ds_read_b128 v[52:55], v12 offset:16384
	ds_read_b128 v[40:43], v10 offset:128
	ds_read_b128 v[56:59], v13 offset:16384
	ds_read_b128 v[44:47], v10 offset:192
	ds_read_b128 v[60:63], v14 offset:16384
	ds_read_u16 v80, v23 offset:0
	ds_read_u16 v81, v23 offset:64
	ds_read_u16 v82, v23 offset:128
	ds_read_u16 v83, v23 offset:192
	s_add_u32 s33, s6, 1
	s_min_u32 s33, s33, 31
	s_add_u32 s36, s6, 2
	s_min_u32 s36, s36, 31
	s_lshl_b32 s7, s33, 14
	s_add_u32 s26, s14, s7
	s_addc_u32 s27, s15, 0
	s_add_i32 m0, s30, 0x10000
	s_nop 0
	global_load_lds_dwordx4 v5, s[26:27]
	s_add_i32 m0, s30, 0x10400
	s_nop 0
	global_load_lds_dwordx4 v6, s[26:27]
	s_lshl_b32 s7, s33, 13
	s_add_u32 s28, s18, s7
	s_addc_u32 s29, s19, 0
	s_add_i32 m0, s31, 0x18000
	s_nop 0
	global_load_lds_dwordx4 v7, s[28:29]
	s_lshl_b32 s7, s36, 14
	s_add_u32 s26, s24, s7
	s_addc_u32 s27, s25, 0
	s_add_u32 s8, s6, 2
	s_and_b32 s8, s8, 3
	s_lshl_b32 s8, s8, 12
	s_add_u32 s8, s8, s32
	s_add_i32 m0, s8, 0x1f400
	s_nop 0
	global_load_lds_dwordx4 v8, s[26:27]
	v_readlane_b32 s37, v24, s6
	s_nop 1
	v_mul_f32_e32 v92, s37, v92
	v_mul_f32_e32 v93, s37, v93
	v_mul_f32_e32 v94, s37, v94
	v_mul_f32_e32 v95, s37, v95
	v_mul_f32_e32 v96, s37, v96
	v_mul_f32_e32 v97, s37, v97
	v_mul_f32_e32 v98, s37, v98
	v_mul_f32_e32 v99, s37, v99
	s_waitcnt lgkmcnt(10)
	v_mfma_f32_16x16x32_bf16 v[84:87], v[48:51], v[32:35], 0
	s_waitcnt lgkmcnt(8)
	v_mfma_f32_16x16x32_bf16 v[84:87], v[52:55], v[36:39], v[84:87]
	s_waitcnt lgkmcnt(6)
	v_mfma_f32_16x16x32_bf16 v[84:87], v[56:59], v[40:43], v[84:87]
	s_waitcnt lgkmcnt(4)
	v_mfma_f32_16x16x32_bf16 v[84:87], v[60:63], v[44:47], v[84:87]
	ds_read_b128 v[64:67], v11 offset:49152
	ds_read_b128 v[68:71], v12 offset:49152
	ds_read_b128 v[72:75], v13 offset:49152
	ds_read_b128 v[76:79], v14 offset:49152
	s_waitcnt lgkmcnt(4)
	v_lshlrev_b32_e32 v80, 16, v80
	v_lshlrev_b32_e32 v81, 16, v81
	v_lshlrev_b32_e32 v82, 16, v82
	v_lshlrev_b32_e32 v83, 16, v83
	v_sub_f32_e32 v26, v80, v84
	v_sub_f32_e32 v27, v81, v85
	v_sub_f32_e32 v28, v82, v86
	v_sub_f32_e32 v29, v83, v87
	v_cvt_pk_bf16_f32 v26, v26, v27
	v_cvt_pk_bf16_f32 v27, v28, v29
	ds_write_b64 v20, v[26:27]
	s_waitcnt vmcnt(10) lgkmcnt(0)
	s_barrier
	ds_read_b128 v[100:103], v19
	ds_read_b128 v[108:111], v15 offset:16384
	ds_read_b128 v[112:115], v15 offset:18432
	ds_read_b128 v[104:107], v19 offset:64
	ds_read_b128 v[116:119], v16 offset:16384
	ds_read_b128 v[120:123], v16 offset:18432
	ds_read_b128 v[124:127], v17 offset:8192
	ds_read_b128 v[128:131], v18 offset:8192
	s_lshl_b32 s7, s36, 14
	s_add_u32 s26, s10, s7
	s_addc_u32 s27, s11, 0
	s_add_i32 m0, s30, 0x4000
	s_nop 0
	global_load_lds_dwordx4 v3, s[26:27]
	s_add_i32 m0, s30, 0x4400
	s_nop 0
	global_load_lds_dwordx4 v4, s[26:27]
	s_lshl_b32 s7, s36, 14
	s_add_u32 s26, s12, s7
	s_addc_u32 s27, s13, 0
	s_add_i32 m0, s30, 0xc000
	s_nop 0
	global_load_lds_dwordx4 v3, s[26:27]
	s_add_i32 m0, s30, 0xc400
	s_nop 0
	global_load_lds_dwordx4 v4, s[26:27]
	v_mfma_f32_16x16x32_bf16 v[88:91], v[32:35], v[64:67], 0
	v_mfma_f32_16x16x32_bf16 v[88:91], v[36:39], v[68:71], v[88:91]
	v_mfma_f32_16x16x32_bf16 v[88:91], v[40:43], v[72:75], v[88:91]
	v_mfma_f32_16x16x32_bf16 v[88:91], v[44:47], v[76:79], v[88:91]
	s_waitcnt lgkmcnt(6)
	v_mfma_f32_16x16x32_bf16 v[92:95], v[108:111], v[100:103], v[92:95]
	s_waitcnt lgkmcnt(5)
	v_mfma_f32_16x16x32_bf16 v[96:99], v[112:115], v[100:103], v[96:99]
	s_waitcnt lgkmcnt(3)
	v_mfma_f32_16x16x32_bf16 v[92:95], v[116:119], v[104:107], v[92:95]
	s_waitcnt lgkmcnt(2)
	v_mfma_f32_16x16x32_bf16 v[96:99], v[120:123], v[104:107], v[96:99]
	s_waitcnt lgkmcnt(1)
	v_mfma_f32_16x16x32_bf16 v[88:91], v[100:103], v[124:127], v[88:91]
	s_waitcnt lgkmcnt(0)
	v_mfma_f32_16x16x32_bf16 v[88:91], v[104:107], v[128:131], v[88:91]
	s_lshl_b32 s7, s6, 14
	s_add_u32 s28, s24, s7
	s_addc_u32 s29, s25, 0
	s_nop 1
	v_cvt_pk_bf16_f32 v26, v92, v93
	v_cvt_pk_bf16_f32 v27, v94, v95
	v_cvt_pk_bf16_f32 v28, v96, v97
	v_cvt_pk_bf16_f32 v29, v98, v99
	ds_write_b64 v21, v[26:27]
	ds_write_b64 v21, v[28:29] offset:32
	v_cvt_pk_bf16_f32 v80, v88, v89
	v_cvt_pk_bf16_f32 v81, v90, v91
	global_store_dwordx2 v9, v[80:81], s[28:29]
	s_add_u32 s6, s6, 1
	s_waitcnt vmcnt(10) lgkmcnt(0)
	s_barrier
	s_cmp_lt_u32 s6, 32
	s_cbranch_scc1 .Lscan_loop
	s_lshl_b32 s56, s77, 5
	s_and_b32 s57, s40, 3
	s_lshl_b32 s72, s40, 5
	s_waitcnt vmcnt(0)
	v_readfirstlane_b32 s3, v194
	s_cmp_gt_u32 s3, 63
	s_barrier
	s_cbranch_scc1 .LBB0_421
	s_waitcnt vmcnt(2)
	v_mbcnt_lo_u32_b32 v0, -1, 0
	v_mbcnt_hi_u32_b32 v0, -1, v0
	s_nop 0
	v_cmp_eq_u32_e32 vcc, 0, v0
	s_and_saveexec_b64 s[6:7], vcc
	s_cbranch_execz .LBB0_420
	s_add_i32 s3, 0, 0x23ff0
	v_mov_b32_e32 v0, s3
	s_waitcnt vmcnt(0) expcnt(0) lgkmcnt(0)
	ds_read_b32 v2, v0
	s_add_i32 s3, 0, 0x23ff4
	v_mov_b32_e32 v0, s3
	ds_read_b32 v0, v0
	s_waitcnt lgkmcnt(1)
	v_cmp_ne_u32_e32 vcc, 0, v2
	s_cbranch_vccnz .LBB0_384
	s_mov_b32 s3, 1
	v_mov_b32_e32 v16, 0
	s_branch .LBB0_372
